# RG-LRU gate math: the four elements of each MFMA result evaluated interleaved and branch-free (both 1-a^2 forms computed, per-lane select) instead of serially
# speedup vs baseline: 1.0193x; 1.0193x over previous
.LBB0_439:
	s_or_b64 exec, exec, s[50:51]
	s_waitcnt lgkmcnt(0)
	s_barrier
	ds_read_b128 v[56:59], v176 offset:11808
	ds_read_b128 v[52:55], v176 offset:11872
	ds_read_b128 v[48:51], v176 offset:11936
	ds_read_b128 v[24:27], v188 offset:39536
	ds_read_b128 v[28:31], v188 offset:49520
	s_waitcnt lgkmcnt(1)
	v_mfma_f32_16x16x32_bf16 v[24:27], v[24:27], v[56:59], 0
	ds_read_b128 v[32:35], v188 offset:39600
	ds_read_b128 v[36:39], v188 offset:49584
	s_waitcnt lgkmcnt(2)
	v_mfma_f32_16x16x32_bf16 v[28:31], v[28:31], v[56:59], 0
	s_waitcnt lgkmcnt(1)
	v_mfma_f32_16x16x32_bf16 v[24:27], v[32:35], v[52:55], v[24:27]
	ds_read_b128 v[32:35], v188 offset:39664
	ds_read_b128 v[40:43], v188 offset:49648
	s_waitcnt lgkmcnt(2)
	v_mfma_f32_16x16x32_bf16 v[28:31], v[36:39], v[52:55], v[28:31]
	s_waitcnt lgkmcnt(1)
	v_mfma_f32_16x16x32_bf16 v[36:39], v[32:35], v[48:51], v[24:27]
	s_waitcnt lgkmcnt(0)
	v_mfma_f32_16x16x32_bf16 v[24:27], v[40:43], v[48:51], v[28:31]
	ds_read_b128 v[40:43], v150 offset:37408
	s_nop 2
	ds_read_b128 v[28:31], v150 offset:37600
	ds_read_b128 v[44:47], v150 offset:37792
	ds_read_b128 v[32:35], v189 offset:25120
	s_waitcnt lgkmcnt(3)
	v_add_f32_e32 v236, v36, v40
	v_add_f32_e32 v237, v37, v41
	v_add_f32_e32 v238, v38, v42
	v_add_f32_e32 v239, v39, v43
	v_mul_f32_e32 v236, 0xbfb8aa3b, v236
	v_mul_f32_e32 v237, 0xbfb8aa3b, v237
	v_mul_f32_e32 v238, 0xbfb8aa3b, v238
	v_mul_f32_e32 v239, 0xbfb8aa3b, v239
	v_exp_f32_e32 v236, v236
	v_exp_f32_e32 v237, v237
	v_exp_f32_e32 v238, v238
	v_exp_f32_e32 v239, v239
	v_add_f32_e32 v236, 1.0, v236
	v_add_f32_e32 v237, 1.0, v237
	v_add_f32_e32 v238, 1.0, v238
	v_add_f32_e32 v239, 1.0, v239
	v_rcp_f32_e32 v236, v236
	v_rcp_f32_e32 v237, v237
	v_rcp_f32_e32 v238, v238
	v_rcp_f32_e32 v239, v239
	s_waitcnt lgkmcnt(1)
	v_mul_f32_e32 v240, v44, v236
	v_mul_f32_e32 v241, v45, v237
	v_mul_f32_e32 v242, v46, v238
	v_mul_f32_e32 v243, v47, v239
	v_mul_f32_e32 v236, 0x3fb8aa3b, v240
	v_mul_f32_e32 v237, 0x3fb8aa3b, v241
	v_mul_f32_e32 v238, 0x3fb8aa3b, v242
	v_mul_f32_e32 v239, 0x3fb8aa3b, v243
	v_exp_f32_e32 v0, v236
	v_exp_f32_e32 v3, v237
	v_exp_f32_e32 v209, v238
	v_exp_f32_e32 v213, v239
	v_add_f32_e32 v240, v240, v240
	v_add_f32_e32 v241, v241, v241
	v_add_f32_e32 v242, v242, v242
	v_add_f32_e32 v243, v243, v243
	v_fmamk_f32 v236, v240, 0x3d2aaaab, v177
	v_fmamk_f32 v237, v241, 0x3d2aaaab, v177
	v_fmamk_f32 v238, v242, 0x3d2aaaab, v177
	v_fmamk_f32 v239, v243, 0x3d2aaaab, v177
	v_fma_f32 v236, v240, v236, 0.5
	v_fma_f32 v237, v241, v237, 0.5
	v_fma_f32 v238, v242, v238, 0.5
	v_fma_f32 v239, v243, v239, 0.5
	v_fma_f32 v236, v240, v236, 1.0
	v_fma_f32 v237, v241, v237, 1.0
	v_fma_f32 v238, v242, v238, 1.0
	v_fma_f32 v239, v243, v239, 1.0
	v_mul_f32_e64 v236, v236, -v240
	v_mul_f32_e64 v237, v237, -v241
	v_mul_f32_e64 v238, v238, -v242
	v_mul_f32_e64 v239, v239, -v243
	v_cmp_nlt_f32_e64 s[0:1], s79, v240
	v_cmp_nlt_f32_e64 s[50:51], s79, v241
	v_fma_f32 v244, -v0, v0, 1.0
	v_fma_f32 v245, -v3, v3, 1.0
	v_cndmask_b32_e64 v2, v236, v244, s[0:1]
	v_cndmask_b32_e64 v206, v237, v245, s[50:51]
	v_cmp_nlt_f32_e64 s[0:1], s79, v242
	v_cmp_nlt_f32_e64 s[50:51], s79, v243
	v_fma_f32 v246, -v209, v209, 1.0
	v_fma_f32 v247, -v213, v213, 1.0
	v_cndmask_b32_e64 v210, v238, v246, s[0:1]
	v_cndmask_b32_e64 v214, v239, v247, s[50:51]
	ds_read_b128 v[36:39], v188 offset:42864
	ds_read_b128 v[40:43], v188 offset:52848
	ds_read_b128 v[44:47], v188 offset:42928
	ds_read_b128 v[60:63], v188 offset:52912
	s_waitcnt lgkmcnt(3)
	v_mfma_f32_16x16x32_bf16 v[36:39], v[36:39], v[56:59], 0
	s_waitcnt lgkmcnt(2)
	v_mfma_f32_16x16x32_bf16 v[40:43], v[40:43], v[56:59], 0
	s_waitcnt lgkmcnt(1)
	v_mfma_f32_16x16x32_bf16 v[36:39], v[44:47], v[52:55], v[36:39]
	ds_read_b128 v[44:47], v188 offset:42992
	ds_read_b128 v[64:67], v188 offset:52976
	s_waitcnt lgkmcnt(2)
	v_mfma_f32_16x16x32_bf16 v[40:43], v[60:63], v[52:55], v[40:43]
	s_waitcnt lgkmcnt(1)
	v_mfma_f32_16x16x32_bf16 v[60:63], v[44:47], v[48:51], v[36:39]
	s_waitcnt lgkmcnt(0)
	v_mfma_f32_16x16x32_bf16 v[36:39], v[64:67], v[48:51], v[40:43]
	ds_read_b128 v[64:67], v150 offset:37472
	s_nop 2
	ds_read_b128 v[40:43], v150 offset:37664
	ds_read_b128 v[68:71], v150 offset:37856
	ds_read_b128 v[44:47], v189 offset:25184
	s_waitcnt lgkmcnt(3)
	v_add_f32_e32 v236, v60, v64
	v_add_f32_e32 v237, v61, v65
	v_add_f32_e32 v238, v62, v66
	v_add_f32_e32 v239, v63, v67
	v_mul_f32_e32 v236, 0xbfb8aa3b, v236
	v_mul_f32_e32 v237, 0xbfb8aa3b, v237
	v_mul_f32_e32 v238, 0xbfb8aa3b, v238
	v_mul_f32_e32 v239, 0xbfb8aa3b, v239
	v_exp_f32_e32 v236, v236
	v_exp_f32_e32 v237, v237
	v_exp_f32_e32 v238, v238
	v_exp_f32_e32 v239, v239
	v_add_f32_e32 v236, 1.0, v236
	v_add_f32_e32 v237, 1.0, v237
	v_add_f32_e32 v238, 1.0, v238
	v_add_f32_e32 v239, 1.0, v239
	v_rcp_f32_e32 v236, v236
	v_rcp_f32_e32 v237, v237
	v_rcp_f32_e32 v238, v238
	v_rcp_f32_e32 v239, v239
	s_waitcnt lgkmcnt(1)
	v_mul_f32_e32 v240, v68, v236
	v_mul_f32_e32 v241, v69, v237
	v_mul_f32_e32 v242, v70, v238
	v_mul_f32_e32 v243, v71, v239
	v_mul_f32_e32 v236, 0x3fb8aa3b, v240
	v_mul_f32_e32 v237, 0x3fb8aa3b, v241
	v_mul_f32_e32 v238, 0x3fb8aa3b, v242
	v_mul_f32_e32 v239, 0x3fb8aa3b, v243
	v_exp_f32_e32 v207, v236
	v_exp_f32_e32 v211, v237
	v_exp_f32_e32 v215, v238
	v_exp_f32_e32 v217, v239
	v_add_f32_e32 v240, v240, v240
	v_add_f32_e32 v241, v241, v241
	v_add_f32_e32 v242, v242, v242
	v_add_f32_e32 v243, v243, v243
	v_fmamk_f32 v236, v240, 0x3d2aaaab, v177
	v_fmamk_f32 v237, v241, 0x3d2aaaab, v177
	v_fmamk_f32 v238, v242, 0x3d2aaaab, v177
	v_fmamk_f32 v239, v243, 0x3d2aaaab, v177
	v_fma_f32 v236, v240, v236, 0.5
	v_fma_f32 v237, v241, v237, 0.5
	v_fma_f32 v238, v242, v238, 0.5
	v_fma_f32 v239, v243, v239, 0.5
	v_fma_f32 v236, v240, v236, 1.0
	v_fma_f32 v237, v241, v237, 1.0
	v_fma_f32 v238, v242, v238, 1.0
	v_fma_f32 v239, v243, v239, 1.0
	v_mul_f32_e64 v236, v236, -v240
	v_mul_f32_e64 v237, v237, -v241
	v_mul_f32_e64 v238, v238, -v242
	v_mul_f32_e64 v239, v239, -v243
	v_cmp_nlt_f32_e64 s[0:1], s79, v240
	v_cmp_nlt_f32_e64 s[50:51], s79, v241
	v_fma_f32 v244, -v207, v207, 1.0
	v_fma_f32 v245, -v211, v211, 1.0
	v_cndmask_b32_e64 v208, v236, v244, s[0:1]
	v_cndmask_b32_e64 v212, v237, v245, s[50:51]
	v_cmp_nlt_f32_e64 s[0:1], s79, v242
	v_cmp_nlt_f32_e64 s[50:51], s79, v243
	v_fma_f32 v246, -v215, v215, 1.0
	v_fma_f32 v247, -v217, v217, 1.0
	v_cndmask_b32_e64 v216, v238, v246, s[0:1]
	v_cndmask_b32_e64 v218, v239, v247, s[50:51]
	ds_read_b128 v[60:63], v188 offset:46192
	ds_read_b128 v[64:67], v188 offset:56176
	s_waitcnt lgkmcnt(1)
	v_mfma_f32_16x16x32_bf16 v[60:63], v[60:63], v[56:59], 0
	s_waitcnt lgkmcnt(0)
	v_mfma_f32_16x16x32_bf16 v[56:59], v[64:67], v[56:59], 0
	ds_read_b128 v[64:67], v188 offset:46256
	ds_read_b128 v[68:71], v188 offset:56240
	s_waitcnt lgkmcnt(1)
	v_mfma_f32_16x16x32_bf16 v[60:63], v[64:67], v[52:55], v[60:63]
	s_waitcnt lgkmcnt(0)
	v_mfma_f32_16x16x32_bf16 v[52:55], v[68:71], v[52:55], v[56:59]
	s_nop 2
	ds_read_b128 v[56:59], v188 offset:46320
	ds_read_b128 v[64:67], v188 offset:56304
	s_waitcnt lgkmcnt(1)
	v_mfma_f32_16x16x32_bf16 v[60:63], v[56:59], v[48:51], v[60:63]
	s_waitcnt lgkmcnt(0)
	v_mfma_f32_16x16x32_bf16 v[48:51], v[64:67], v[48:51], v[52:55]
	ds_read_b128 v[64:67], v150 offset:37536
	s_nop 1
	ds_read_b128 v[52:55], v150 offset:37728
	ds_read_b128 v[68:71], v150 offset:37920
	ds_read_b128 v[56:59], v189 offset:25248
	s_waitcnt lgkmcnt(3)
	v_add_f32_e32 v236, v60, v64
	v_add_f32_e32 v237, v61, v65
	v_add_f32_e32 v238, v62, v66
	v_add_f32_e32 v239, v63, v67
	v_mul_f32_e32 v236, 0xbfb8aa3b, v236
	v_mul_f32_e32 v237, 0xbfb8aa3b, v237
	v_mul_f32_e32 v238, 0xbfb8aa3b, v238
	v_mul_f32_e32 v239, 0xbfb8aa3b, v239
	v_exp_f32_e32 v236, v236
	v_exp_f32_e32 v237, v237
	v_exp_f32_e32 v238, v238
	v_exp_f32_e32 v239, v239
	v_add_f32_e32 v236, 1.0, v236
	v_add_f32_e32 v237, 1.0, v237
	v_add_f32_e32 v238, 1.0, v238
	v_add_f32_e32 v239, 1.0, v239
	v_rcp_f32_e32 v236, v236
	v_rcp_f32_e32 v237, v237
	v_rcp_f32_e32 v238, v238
	v_rcp_f32_e32 v239, v239
	s_waitcnt lgkmcnt(1)
	v_mul_f32_e32 v240, v68, v236
	v_mul_f32_e32 v241, v69, v237
	v_mul_f32_e32 v242, v70, v238
	v_mul_f32_e32 v243, v71, v239
	v_mul_f32_e32 v236, 0x3fb8aa3b, v240
	v_mul_f32_e32 v237, 0x3fb8aa3b, v241
	v_mul_f32_e32 v238, 0x3fb8aa3b, v242
	v_mul_f32_e32 v239, 0x3fb8aa3b, v243
	v_exp_f32_e32 v60, v236
	v_exp_f32_e32 v61, v237
	v_exp_f32_e32 v62, v238
	v_exp_f32_e32 v63, v239
	v_add_f32_e32 v240, v240, v240
	v_add_f32_e32 v241, v241, v241
	v_add_f32_e32 v242, v242, v242
	v_add_f32_e32 v243, v243, v243
	v_fmamk_f32 v236, v240, 0x3d2aaaab, v177
	v_fmamk_f32 v237, v241, 0x3d2aaaab, v177
	v_fmamk_f32 v238, v242, 0x3d2aaaab, v177
	v_fmamk_f32 v239, v243, 0x3d2aaaab, v177
	v_fma_f32 v236, v240, v236, 0.5
	v_fma_f32 v237, v241, v237, 0.5
	v_fma_f32 v238, v242, v238, 0.5
	v_fma_f32 v239, v243, v239, 0.5
	v_fma_f32 v236, v240, v236, 1.0
	v_fma_f32 v237, v241, v237, 1.0
	v_fma_f32 v238, v242, v238, 1.0
	v_fma_f32 v239, v243, v239, 1.0
	v_mul_f32_e64 v236, v236, -v240
	v_mul_f32_e64 v237, v237, -v241
	v_mul_f32_e64 v238, v238, -v242
	v_mul_f32_e64 v239, v239, -v243
	v_cmp_nlt_f32_e64 s[0:1], s79, v240
	v_cmp_nlt_f32_e64 s[50:51], s79, v241
	v_fma_f32 v244, -v60, v60, 1.0
	v_fma_f32 v245, -v61, v61, 1.0
	v_cndmask_b32_e64 v64, v236, v244, s[0:1]
	v_cndmask_b32_e64 v65, v237, v245, s[50:51]
	v_cmp_nlt_f32_e64 s[0:1], s79, v242
	v_cmp_nlt_f32_e64 s[50:51], s79, v243
	v_fma_f32 v246, -v62, v62, 1.0
	v_fma_f32 v247, -v63, v63, 1.0
	v_cndmask_b32_e64 v66, v238, v246, s[0:1]
	v_cndmask_b32_e64 v67, v239, v247, s[50:51]
	v_add_f32_e32 v27, v27, v31
	v_mul_f32_e32 v27, 0xbfb8aa3b, v27
	v_exp_f32_e32 v31, v27
	v_sqrt_f32_e32 v69, v214
	v_or_b32_e32 v68, s33, v142
	v_add_f32_e32 v26, v26, v30
	v_add_f32_e32 v31, 1.0, v31
	v_rcp_f32_e32 v31, v31
	v_cmp_ne_u32_e64 s[0:1], 0, v68
	v_mul_f32_e32 v26, 0xbfb8aa3b, v26
	s_or_b64 s[50:51], s[30:31], s[0:1]
	v_exp_f32_e32 v26, v26
	v_cndmask_b32_e64 v68, 1.0, v69, s[50:51]
	v_mul_f32_e32 v31, v31, v68
	v_mul_f32_e32 v30, v35, v31
	v_cndmask_b32_e64 v31, v30, 0, s[46:47]
	v_sqrt_f32_e32 v30, v210
	v_add_f32_e32 v26, 1.0, v26
	v_rcp_f32_e32 v35, v26
	v_add_f32_e32 v25, v25, v29
	v_mul_f32_e32 v25, 0xbfb8aa3b, v25
	v_exp_f32_e32 v25, v25
	v_cndmask_b32_e64 v30, 1.0, v30, s[50:51]
	v_mul_f32_e32 v29, v35, v30
	v_mul_f32_e32 v29, v34, v29
	v_add_f32_e32 v24, v24, v28
	v_cndmask_b32_e64 v30, v29, 0, s[46:47]
	v_add_f32_e32 v25, 1.0, v25
	v_sqrt_f32_e32 v29, v206
	v_mul_f32_e32 v24, 0xbfb8aa3b, v24
	v_rcp_f32_e32 v25, v25
	v_exp_f32_e32 v24, v24
	v_cndmask_b32_e64 v28, 1.0, v29, s[50:51]
	v_cndmask_b32_e64 v3, v3, 1.0, s[46:47]
	v_mul_f32_e32 v25, v25, v28
	v_add_f32_e32 v24, 1.0, v24
	v_sqrt_f32_e32 v28, v2
	v_rcp_f32_e32 v24, v24
	v_cndmask_b32_e64 v2, v0, 1.0, s[46:47]
	v_mul_f32_e32 v25, v33, v25
	v_cndmask_b32_e64 v0, 1.0, v28, s[50:51]
	v_mul_f32_e32 v0, v24, v0
	v_mul_f32_e32 v0, v32, v0
	v_cndmask_b32_e64 v25, v25, 0, s[46:47]
	v_cndmask_b32_e64 v24, v0, 0, s[46:47]
	v_mov_b32_e32 v28, 1.0
	v_mov_b32_e32 v32, v1
	v_mov_b32_e32 v29, 1.0
	v_mov_b32_e32 v33, v1
	v_mov_b32_dpp v28, v2 row_shr:1 row_mask:0xf bank_mask:0xf
	v_mov_b32_dpp v32, v24 row_shr:1 row_mask:0xf bank_mask:0xf
	v_mov_b32_dpp v29, v3 row_shr:1 row_mask:0xf bank_mask:0xf
	v_mov_b32_dpp v33, v25 row_shr:1 row_mask:0xf bank_mask:0xf
	v_pk_mul_f32 v[28:29], v[2:3], v[28:29]
	v_pk_fma_f32 v[2:3], v[2:3], v[32:33], v[24:25]
	v_mov_b32_e32 v24, v1
	v_mov_b32_e32 v25, v1
	v_mov_b32_e32 v34, 1.0
	v_mov_b32_dpp v24, v2 row_shr:2 row_mask:0xf bank_mask:0xf
	v_mov_b32_e32 v35, 1.0
	v_mov_b32_dpp v25, v3 row_shr:2 row_mask:0xf bank_mask:0xf
	v_mov_b32_dpp v34, v28 row_shr:2 row_mask:0xf bank_mask:0xf
	v_mov_b32_dpp v35, v29 row_shr:2 row_mask:0xf bank_mask:0xf
	v_pk_fma_f32 v[2:3], v[28:29], v[24:25], v[2:3]
	v_mov_b32_e32 v24, v1
	v_mov_b32_e32 v25, v1
	v_pk_mul_f32 v[32:33], v[28:29], v[34:35]
	v_mov_b32_e32 v34, 1.0
	v_mov_b32_dpp v24, v2 row_shr:4 row_mask:0xf bank_mask:0xf
	v_mov_b32_e32 v35, 1.0
	v_mov_b32_dpp v25, v3 row_shr:4 row_mask:0xf bank_mask:0xf
	v_mov_b32_dpp v34, v32 row_shr:4 row_mask:0xf bank_mask:0xf
	v_mov_b32_dpp v35, v33 row_shr:4 row_mask:0xf bank_mask:0xf
	v_pk_fma_f32 v[2:3], v[32:33], v[24:25], v[2:3]
	v_mov_b32_e32 v24, v1
	v_mov_b32_e32 v25, v1
	v_pk_mul_f32 v[28:29], v[32:33], v[34:35]
	v_mov_b32_dpp v24, v2 row_shr:8 row_mask:0xf bank_mask:0xf
	v_mov_b32_dpp v25, v3 row_shr:8 row_mask:0xf bank_mask:0xf
	v_cndmask_b32_e64 v27, v213, 1.0, s[46:47]
	v_cndmask_b32_e64 v26, v209, 1.0, s[46:47]
	v_mov_b32_e32 v34, 1.0
	v_mov_b32_e32 v35, 1.0
	v_pk_fma_f32 v[24:25], v[28:29], v[24:25], v[2:3]
	v_mov_b32_e32 v2, 1.0
	v_mov_b32_e32 v32, v1
	v_mov_b32_e32 v3, 1.0
	v_mov_b32_e32 v33, v1
	v_mov_b32_dpp v34, v28 row_shr:8 row_mask:0xf bank_mask:0xf
	v_mov_b32_dpp v35, v29 row_shr:8 row_mask:0xf bank_mask:0xf
	v_mov_b32_dpp v2, v26 row_shr:1 row_mask:0xf bank_mask:0xf
	v_mov_b32_dpp v32, v30 row_shr:1 row_mask:0xf bank_mask:0xf
	v_mov_b32_dpp v3, v27 row_shr:1 row_mask:0xf bank_mask:0xf
	v_mov_b32_dpp v33, v31 row_shr:1 row_mask:0xf bank_mask:0xf
	v_pk_mul_f32 v[28:29], v[28:29], v[34:35]
	v_pk_mul_f32 v[2:3], v[26:27], v[2:3]
	v_mov_b32_e32 v34, 1.0
	v_pk_fma_f32 v[26:27], v[26:27], v[32:33], v[30:31]
	v_mov_b32_e32 v30, v1
	v_mov_b32_e32 v35, 1.0
	v_mov_b32_e32 v31, v1
	v_mov_b32_dpp v34, v2 row_shr:2 row_mask:0xf bank_mask:0xf
	v_mov_b32_dpp v30, v26 row_shr:2 row_mask:0xf bank_mask:0xf
	v_mov_b32_dpp v35, v3 row_shr:2 row_mask:0xf bank_mask:0xf
	v_mov_b32_dpp v31, v27 row_shr:2 row_mask:0xf bank_mask:0xf
	v_pk_mul_f32 v[32:33], v[2:3], v[34:35]
	v_mov_b32_e32 v34, 1.0
	v_pk_fma_f32 v[2:3], v[2:3], v[30:31], v[26:27]
	v_mov_b32_e32 v26, v1
	v_mov_b32_e32 v35, 1.0
	v_mov_b32_e32 v27, v1
	v_mov_b32_dpp v34, v32 row_shr:4 row_mask:0xf bank_mask:0xf
	v_mov_b32_dpp v26, v2 row_shr:4 row_mask:0xf bank_mask:0xf
	v_mov_b32_dpp v35, v33 row_shr:4 row_mask:0xf bank_mask:0xf
	v_mov_b32_dpp v27, v3 row_shr:4 row_mask:0xf bank_mask:0xf
	v_pk_mul_f32 v[30:31], v[32:33], v[34:35]
	v_mov_b32_e32 v34, 1.0
	v_pk_fma_f32 v[2:3], v[32:33], v[26:27], v[2:3]
	v_mov_b32_e32 v26, v1
	v_mov_b32_e32 v27, v1
	v_mov_b32_e32 v35, 1.0
	v_mov_b32_dpp v34, v30 row_shr:8 row_mask:0xf bank_mask:0xf
	v_mov_b32_dpp v26, v2 row_shr:8 row_mask:0xf bank_mask:0xf
	v_mov_b32_dpp v27, v3 row_shr:8 row_mask:0xf bank_mask:0xf
	v_mov_b32_dpp v35, v31 row_shr:8 row_mask:0xf bank_mask:0xf
	v_pk_fma_f32 v[26:27], v[30:31], v[26:27], v[2:3]
	v_pk_mul_f32 v[30:31], v[30:31], v[34:35]
	s_and_saveexec_b64 s[0:1], s[18:19]
	s_cbranch_execz .LBB0_489
	ds_write_b128 v153, v[28:31] offset:37984
	ds_write_b128 v153, v[24:27] offset:38752
